# neighbourhood attention: no static priority for waves 0-3 (s_setprio 2 replaced by s_nop 0)
# baseline (speedup 1.0000x reference)
.LBB0_434:
	s_and_b64 vcc, exec, s[10:11]
	s_cbranch_vccz .LBB0_509
	v_readlane_b32 s6, v252, 60
	v_readlane_b32 s7, v252, 61
	v_mov_b32_e32 v136, v206
	s_andn2_b64 vcc, exec, s[6:7]
	s_cbranch_vccnz .LBB0_437
	s_nop 0
